# stack plus gmlp: K-loop loads hoisted in two groups of 12 per iteration and epilogue loads issued once
# speedup vs baseline: 1.0009x; 1.0009x over previous
; #define MFMA32(a, b, c) __builtin_amdgcn_mfma_f32_32x32x16_bf16((a), (b), (c), 0, 0, 0)
; __device__ __forceinline__ void gmlp_unit(const bf16* GVT, const bf16* U, const float* wsp, const float* bsp, const float* gain, bf16* OGM, int unit, LAS unsigned char* lds, int tid, int wave, int lane) {
;     ...
;     for (int ks = 0; ks < nks; ++ks) {
;         const bf16* apk = ap + (ks >> 1) * (256 * 32) + 16 * (ks & 1);
;         const bf16x8 a0 = *(const bf16x8*)apk, a1 = *(const bf16x8*)(apk + 32 * 32);
;         const int pb = 16 * ks + 8 * hh;
;         float rs[8];
; #pragma unroll
;         for (int j = 0; j < 8; ++j) rs[j] = rstd[pb + j];
; #pragma unroll
;         for (int nt = 0; nt < 2; ++nt) {
;             const int t = 64 * th + 32 * nt + r; const float* wq = wrow + (size_t)t * 128 + 16 * ks;
;             const f32x4 w0 = *(const f32x4*)wq, w1 = *(const f32x4*)(wq + 4); float bv[8];
; #pragma unroll
;             for (int j = 0; j < 4; ++j) { bv[j] = (pb + j <= t) ? w0[j] * rs[j] : 0.f; bv[4 + j] = (pb + 4 + j <= t) ? w1[j] * rs[4 + j] : 0.f; }
;             const bf16x8 bf = pack8(bv);
;             acc[0][nt] = MFMA32(a0, bf, acc[0][nt]); acc[1][nt] = MFMA32(a1, bf, acc[1][nt]);
;         }
;     }
.LBB0_105:
	s_add_i32 s94, s9, 0xffffd000
	v_lshl_add_u64 v[84:85], s[94:95], 1, v[112:113]
	s_sub_i32 s94, s12, 48
	v_lshl_add_u64 v[74:75], s[94:95], 2, v[92:93]
	v_lshl_add_u64 v[72:73], v[74:75], 0, v[178:179]
	v_mov_b32_e32 v158, v110
	v_mov_b32_e32 v159, 0
	v_lshl_add_u64 v[148:149], v[74:75], 0, v[158:159]
	global_load_dwordx4 v[192:195], v[84:85], off
	global_load_dwordx4 v[196:199], v[84:85], off offset:2048
	global_load_dwordx4 v[200:203], v[72:73], off offset:16
	global_load_dwordx4 v[204:207], v[72:73], off
	global_load_dwordx4 v[208:211], v[148:149], off offset:16
	global_load_dwordx4 v[212:215], v[148:149], off
	global_load_dwordx4 v[216:219], v[84:85], off offset:32
	global_load_dwordx4 v[220:223], v[84:85], off offset:2080
	global_load_dwordx4 v[232:235], v[72:73], off offset:80
	global_load_dwordx4 v[236:239], v[72:73], off offset:64
	global_load_dwordx4 v[240:243], v[148:149], off offset:80
	global_load_dwordx4 v[244:247], v[148:149], off offset:64
	s_waitcnt vmcnt(0)
	s_nop 4
	v_mov_b32_e32 v64, v192
	v_mov_b32_e32 v65, v193
	v_mov_b32_e32 v66, v194
	v_mov_b32_e32 v67, v195
	s_nop 4
	v_mov_b32_e32 v68, v196
	v_mov_b32_e32 v69, v197
	v_mov_b32_e32 v70, v198
	v_mov_b32_e32 v71, v199
	ds_read_b128 v[76:79], v119
	ds_read_b128 v[80:83], v119 offset:16
	s_nop 4
	v_mov_b32_e32 v122, v200
	v_mov_b32_e32 v123, v201
	v_mov_b32_e32 v124, v202
	v_mov_b32_e32 v125, v203
	s_nop 4
	v_mov_b32_e32 v126, v204
	v_mov_b32_e32 v127, v205
	v_mov_b32_e32 v128, v206
	v_mov_b32_e32 v129, v207
	v_add_u32_e32 v120, s12, v116
	v_subrev_u32_e32 v114, 48, v120
	v_cmp_le_u32_e64 s[6:7], v114, v94
	s_add_i32 s94, s9, 0xfffff000
	s_mov_b32 s13, s95
	s_add_i32 s15, s15, -4
	s_waitcnt lgkmcnt(1)
	v_mul_f32_e32 v111, v76, v126
	v_cndmask_b32_e64 v111, 0, v111, s[6:7]
	v_cmp_lt_u32_e64 s[6:7], v114, v94
	v_mul_f32_e32 v115, v77, v127
	v_or_b32_e32 v127, 4, v114
	v_cndmask_b32_e64 v115, 0, v115, s[6:7]
	v_cvt_pk_bf16_f32 v130, v111, v115
	v_mov_b32_e32 v111, v179
	v_lshl_add_u64 v[74:75], v[74:75], 0, v[110:111]
	s_nop 4
	v_mov_b32_e32 v134, v208
	v_mov_b32_e32 v135, v209
	v_mov_b32_e32 v136, v210
	v_mov_b32_e32 v137, v211
	s_nop 4
	v_mov_b32_e32 v138, v212
	v_mov_b32_e32 v139, v213
	v_mov_b32_e32 v140, v214
	v_mov_b32_e32 v141, v215
	v_cmp_le_u32_e64 s[6:7], v114, v96
	v_or_b32_e32 v126, 5, v114
	v_mul_f32_e32 v76, v76, v138
	v_cndmask_b32_e64 v115, 0, v76, s[6:7]
	v_cmp_lt_u32_e64 s[6:7], v114, v96
	v_mul_f32_e32 v76, v77, v139
	s_nop 0
	v_cndmask_b32_e64 v121, 0, v76, s[6:7]
	s_waitcnt lgkmcnt(0)
	v_pk_mul_f32 v[76:77], v[80:81], v[122:123]
	v_cmp_le_u32_e64 s[6:7], v127, v94
	v_cvt_pk_bf16_f32 v76, v76, v77
	v_or_b32_e32 v123, 2, v114
	v_cndmask_b32_e64 v77, 0, v76, s[6:7]
	v_cmp_le_u32_e64 s[6:7], v126, v89
	v_lshrrev_b32_e32 v76, 16, v76
	v_or_b32_e32 v122, 3, v114
	v_cndmask_b32_e64 v76, 0, v76, s[6:7]
	v_perm_b32 v132, v76, v77, s52
	v_pk_mul_f32 v[76:77], v[78:79], v[128:129]
	v_cmp_le_u32_e64 s[6:7], v123, v94
	v_cvt_pk_bf16_f32 v76, v76, v77
	v_or_b32_e32 v128, 7, v114
	v_cndmask_b32_e64 v77, 0, v76, s[6:7]
	v_lshrrev_b32_e32 v76, 16, v76
	v_cmp_le_u32_e64 s[6:7], v122, v89
	v_or_b32_e32 v114, 6, v114
	v_pk_mul_f32 v[78:79], v[78:79], v[140:141]
	v_cndmask_b32_e64 v76, 0, v76, s[6:7]
	v_perm_b32 v131, v76, v77, s52
	v_pk_mul_f32 v[76:77], v[82:83], v[124:125]
	v_cmp_le_u32_e64 s[6:7], v114, v94
	v_cvt_pk_bf16_f32 v76, v76, v77
	v_pk_mul_f32 v[80:81], v[80:81], v[134:135]
	v_cndmask_b32_e64 v77, 0, v76, s[6:7]
	v_lshrrev_b32_e32 v76, 16, v76
	v_cmp_le_u32_e64 s[6:7], v128, v89
	v_pk_mul_f32 v[82:83], v[82:83], v[136:137]
	s_nop 0
	v_cndmask_b32_e64 v76, 0, v76, s[6:7]
	v_perm_b32 v133, v76, v77, s52
	v_cvt_pk_bf16_f32 v77, v78, v79
	v_cmp_le_u32_e64 s[6:7], v123, v96
	v_cvt_pk_bf16_f32 v76, v115, v121
	v_mfma_f32_32x32x16_bf16 v[48:63], v[64:67], v[130:133], v[48:63]
	v_cndmask_b32_e64 v78, 0, v77, s[6:7]
	v_lshrrev_b32_e32 v77, 16, v77
	v_cmp_le_u32_e64 s[6:7], v122, v87
	s_nop 1
	v_cndmask_b32_e64 v77, 0, v77, s[6:7]
	v_perm_b32 v77, v77, v78, s52
	v_cvt_pk_bf16_f32 v78, v80, v81
	v_cmp_le_u32_e64 s[6:7], v127, v96
	v_mfma_f32_32x32x16_bf16 v[16:31], v[68:71], v[130:133], v[16:31]
	s_nop 0
	v_cndmask_b32_e64 v79, 0, v78, s[6:7]
	v_cmp_le_u32_e64 s[6:7], v126, v87
	v_lshrrev_b32_e32 v78, 16, v78
	s_nop 0
	v_cndmask_b32_e64 v78, 0, v78, s[6:7]
	v_perm_b32 v78, v78, v79, s52
	v_cvt_pk_bf16_f32 v79, v82, v83
	v_cmp_le_u32_e64 s[6:7], v114, v96
	s_nop 1
	v_cndmask_b32_e64 v80, 0, v79, s[6:7]
	v_lshrrev_b32_e32 v79, 16, v79
	v_cmp_le_u32_e64 s[6:7], v128, v87
	s_nop 1
	v_cndmask_b32_e64 v79, 0, v79, s[6:7]
	v_perm_b32 v79, v79, v80, s52
	s_nop 1
	v_mfma_f32_32x32x16_bf16 v[32:47], v[64:67], v[76:79], v[32:47]
	v_mfma_f32_32x32x16_bf16 v[0:15], v[68:71], v[76:79], v[0:15]
	s_nop 4
	v_mov_b32_e32 v64, v216
	v_mov_b32_e32 v65, v217
	v_mov_b32_e32 v66, v218
	v_mov_b32_e32 v67, v219
	s_nop 4
	v_mov_b32_e32 v68, v220
	v_mov_b32_e32 v69, v221
	v_mov_b32_e32 v70, v222
	v_mov_b32_e32 v71, v223
	ds_read_b128 v[76:79], v119 offset:64
	s_nop 4
	v_mov_b32_e32 v80, v232
	v_mov_b32_e32 v81, v233
	v_mov_b32_e32 v82, v234
	v_mov_b32_e32 v83, v235
	s_nop 4
	v_mov_b32_e32 v122, v236
	v_mov_b32_e32 v123, v237
	v_mov_b32_e32 v124, v238
	v_mov_b32_e32 v125, v239
	s_nop 4
	v_mov_b32_e32 v126, v240
	v_mov_b32_e32 v127, v241
	v_mov_b32_e32 v128, v242
	v_mov_b32_e32 v129, v243
	s_nop 4
	v_mov_b32_e32 v130, v244
	v_mov_b32_e32 v131, v245
	v_mov_b32_e32 v132, v246
	v_mov_b32_e32 v133, v247
	v_subrev_u32_e32 v84, 32, v120
	ds_read_b128 v[134:137], v119 offset:80
	v_cmp_le_u32_e64 s[6:7], v84, v94
	v_or_b32_e32 v121, 4, v84
	v_or_b32_e32 v115, 5, v84
	s_waitcnt lgkmcnt(0)
; #define MFMA32(a, b, c) __builtin_amdgcn_mfma_f32_32x32x16_bf16((a), (b), (c), 0, 0, 0)
; __device__ __forceinline__ void gmlp_unit(const bf16* GVT, const bf16* U, const float* wsp, const float* bsp, const float* gain, bf16* OGM, int unit, LAS unsigned char* lds, int tid, int wave, int lane) {
;     ...
;     for (int ks = 0; ks < nks; ++ks) {
;         const bf16* apk = ap + (ks >> 1) * (256 * 32) + 16 * (ks & 1);
;         const bf16x8 a0 = *(const bf16x8*)apk, a1 = *(const bf16x8*)(apk + 32 * 32);
;         const int pb = 16 * ks + 8 * hh;
;         float rs[8];
; #pragma unroll
;         for (int j = 0; j < 8; ++j) rs[j] = rstd[pb + j];
; #pragma unroll
;         for (int nt = 0; nt < 2; ++nt) {
;             const int t = 64 * th + 32 * nt + r; const float* wq = wrow + (size_t)t * 128 + 16 * ks;
;             const f32x4 w0 = *(const f32x4*)wq, w1 = *(const f32x4*)(wq + 4); float bv[8];
; #pragma unroll
;             for (int j = 0; j < 4; ++j) { bv[j] = (pb + j <= t) ? w0[j] * rs[j] : 0.f; bv[4 + j] = (pb + 4 + j <= t) ? w1[j] * rs[4 + j] : 0.f; }
;             const bf16x8 bf = pack8(bv);
;             acc[0][nt] = MFMA32(a0, bf, acc[0][nt]); acc[1][nt] = MFMA32(a1, bf, acc[1][nt]);
;         }
;     }
	v_pk_mul_f32 v[74:75], v[134:135], v[80:81]
	v_mul_f32_e32 v72, v76, v122
	v_cndmask_b32_e64 v72, 0, v72, s[6:7]
	v_cmp_lt_u32_e64 s[6:7], v84, v94
	v_mul_f32_e32 v73, v77, v123
	v_or_b32_e32 v123, 2, v84
	v_cndmask_b32_e64 v73, 0, v73, s[6:7]
	v_cvt_pk_bf16_f32 v72, v72, v73
	v_mul_f32_e32 v73, v76, v130
	v_cmp_le_u32_e64 s[6:7], v84, v96
	v_pk_mul_f32 v[80:81], v[78:79], v[124:125]
	v_or_b32_e32 v122, 3, v84
	v_cndmask_b32_e64 v85, 0, v73, s[6:7]
	v_cmp_lt_u32_e64 s[6:7], v84, v96
	v_mul_f32_e32 v73, v77, v131
	v_or_b32_e32 v124, 7, v84
	v_cndmask_b32_e64 v114, 0, v73, s[6:7]
	v_cvt_pk_bf16_f32 v73, v74, v75
	v_cmp_le_u32_e64 s[6:7], v121, v94
	v_or_b32_e32 v84, 6, v84
	v_pk_mul_f32 v[78:79], v[78:79], v[132:133]
	v_cndmask_b32_e64 v74, 0, v73, s[6:7]
	v_cmp_le_u32_e64 s[6:7], v115, v89
	v_lshrrev_b32_e32 v73, 16, v73
	v_pk_mul_f32 v[76:77], v[134:135], v[126:127]
	v_cndmask_b32_e64 v73, 0, v73, s[6:7]
	v_perm_b32 v74, v73, v74, s52
	v_cvt_pk_bf16_f32 v73, v80, v81
	v_cmp_le_u32_e64 s[6:7], v123, v94
	v_pk_mul_f32 v[80:81], v[136:137], v[82:83]
	s_nop 0
	v_cndmask_b32_e64 v75, 0, v73, s[6:7]
	v_lshrrev_b32_e32 v73, 16, v73
	v_cmp_le_u32_e64 s[6:7], v122, v89
	s_nop 1
	v_cndmask_b32_e64 v73, 0, v73, s[6:7]
	v_perm_b32 v73, v73, v75, s52
	v_cvt_pk_bf16_f32 v75, v80, v81
	v_cmp_le_u32_e64 s[6:7], v84, v94
	s_nop 1
	v_cndmask_b32_e64 v80, 0, v75, s[6:7]
	v_lshrrev_b32_e32 v75, 16, v75
	v_cmp_le_u32_e64 s[6:7], v124, v89
	s_nop 1
	v_cndmask_b32_e64 v75, 0, v75, s[6:7]
	v_perm_b32 v75, v75, v80, s52
	v_cmp_le_u32_e64 s[6:7], v123, v96
	v_pk_mul_f32 v[80:81], v[136:137], v[128:129]
	v_mfma_f32_32x32x16_bf16 v[48:63], v[64:67], v[72:75], v[48:63]
	v_mfma_f32_32x32x16_bf16 v[16:31], v[68:71], v[72:75], v[16:31]
	v_cvt_pk_bf16_f32 v73, v78, v79
	v_cndmask_b32_e64 v74, 0, v73, s[6:7]
	v_lshrrev_b32_e32 v73, 16, v73
	v_cmp_le_u32_e64 s[6:7], v122, v87
	v_cvt_pk_bf16_f32 v72, v85, v114
	v_add_u32_e32 v114, -16, v120
	v_cndmask_b32_e64 v73, 0, v73, s[6:7]
	v_perm_b32 v73, v73, v74, s52
	v_cvt_pk_bf16_f32 v74, v76, v77
	v_cmp_le_u32_e64 s[6:7], v121, v96
	v_or_b32_e32 v121, 2, v114
	s_nop 0
	v_cndmask_b32_e64 v75, 0, v74, s[6:7]
	v_cmp_le_u32_e64 s[6:7], v115, v87
	v_lshrrev_b32_e32 v74, 16, v74
	v_or_b32_e32 v115, 3, v114
	v_cndmask_b32_e64 v74, 0, v74, s[6:7]
	v_perm_b32 v74, v74, v75, s52
	v_cvt_pk_bf16_f32 v75, v80, v81
	v_cmp_le_u32_e64 s[6:7], v84, v96
	s_nop 1
	v_cndmask_b32_e64 v76, 0, v75, s[6:7]
	v_lshrrev_b32_e32 v75, 16, v75
	v_cmp_le_u32_e64 s[6:7], v124, v87
	s_nop 1
	v_cndmask_b32_e64 v75, 0, v75, s[6:7]
	v_perm_b32 v75, v75, v76, s52
	v_cmp_le_u32_e64 s[6:7], v114, v94
	s_nop 0
	v_mfma_f32_32x32x16_bf16 v[0:15], v[68:71], v[72:75], v[0:15]
	v_lshl_add_u64 v[68:69], s[94:95], 1, v[112:113]
	s_add_i32 s94, s12, -16
	v_lshl_add_u64 v[84:85], s[94:95], 2, v[92:93]
	v_lshl_add_u64 v[80:81], v[84:85], 0, v[178:179]
	v_mov_b32_e32 v158, v110
	v_mov_b32_e32 v159, 0
	v_lshl_add_u64 v[148:149], v[84:85], 0, v[158:159]
	s_and_b32 s94, s9, 0x7fffe000
	s_lshl_b32 s94, s94, 1
	v_lshl_add_u64 v[150:151], v[112:113], 0, s[94:95]
	v_lshl_add_u64 v[152:153], s[12:13], 2, v[92:93]
	v_lshl_add_u64 v[154:155], v[152:153], 0, v[178:179]
	v_lshl_add_u64 v[156:157], v[152:153], 0, v[158:159]
	global_load_dwordx4 v[192:195], v[68:69], off
	global_load_dwordx4 v[196:199], v[68:69], off offset:2048
	global_load_dwordx4 v[200:203], v[80:81], off offset:16
	global_load_dwordx4 v[204:207], v[80:81], off
	global_load_dwordx4 v[208:211], v[148:149], off offset:16
	global_load_dwordx4 v[212:215], v[148:149], off
	global_load_dwordx4 v[216:219], v[150:151], off offset:32
	global_load_dwordx4 v[220:223], v[150:151], off offset:2080
	global_load_dwordx4 v[232:235], v[154:155], off offset:16
	global_load_dwordx4 v[236:239], v[154:155], off
	global_load_dwordx4 v[240:243], v[156:157], off offset:16
	global_load_dwordx4 v[244:247], v[156:157], off
	s_waitcnt vmcnt(0)
	v_mfma_f32_32x32x16_bf16 v[32:47], v[64:67], v[72:75], v[32:47]
	s_nop 4
	v_mov_b32_e32 v64, v192
	v_mov_b32_e32 v65, v193
	v_mov_b32_e32 v66, v194
	v_mov_b32_e32 v67, v195
	s_nop 0
	s_nop 4
	v_mov_b32_e32 v68, v196
	v_mov_b32_e32 v69, v197
	v_mov_b32_e32 v70, v198
	v_mov_b32_e32 v71, v199
	ds_read_b128 v[72:75], v119 offset:128
	s_nop 4
	v_mov_b32_e32 v76, v200
	v_mov_b32_e32 v77, v201
	v_mov_b32_e32 v78, v202
	v_mov_b32_e32 v79, v203
	s_nop 0
	s_nop 4
	v_mov_b32_e32 v80, v204
	v_mov_b32_e32 v81, v205
	v_mov_b32_e32 v82, v206
	v_mov_b32_e32 v83, v207
	s_waitcnt lgkmcnt(0)
	v_mul_f32_e32 v80, v72, v80
	v_cndmask_b32_e64 v80, 0, v80, s[6:7]
	v_cmp_lt_u32_e64 s[6:7], v114, v94
	v_mul_f32_e32 v81, v73, v81
	s_nop 0
	v_cndmask_b32_e64 v81, 0, v81, s[6:7]
	v_cvt_pk_bf16_f32 v122, v80, v81
	v_lshl_add_u64 v[80:81], v[84:85], 0, v[110:111]
	s_nop 4
	v_mov_b32_e32 v126, v208
	v_mov_b32_e32 v127, v209
	v_mov_b32_e32 v128, v210
	v_mov_b32_e32 v129, v211
	s_nop 4
	v_mov_b32_e32 v130, v212
	v_mov_b32_e32 v131, v213
	v_mov_b32_e32 v132, v214
	v_mov_b32_e32 v133, v215
	ds_read_b128 v[134:137], v119 offset:144
	v_cmp_le_u32_e64 s[6:7], v114, v96
	v_or_b32_e32 v85, 4, v114
	v_or_b32_e32 v84, 5, v114
	v_mul_f32_e32 v72, v72, v130
	v_cndmask_b32_e64 v80, 0, v72, s[6:7]
	v_cmp_lt_u32_e64 s[6:7], v114, v96
	v_mul_f32_e32 v72, v73, v131
	s_nop 0
	v_cndmask_b32_e64 v81, 0, v72, s[6:7]
	s_waitcnt lgkmcnt(0)
; #define MFMA32(a, b, c) __builtin_amdgcn_mfma_f32_32x32x16_bf16((a), (b), (c), 0, 0, 0)
; __device__ __forceinline__ void gmlp_unit(const bf16* GVT, const bf16* U, const float* wsp, const float* bsp, const float* gain, bf16* OGM, int unit, LAS unsigned char* lds, int tid, int wave, int lane) {
;     ...
;     for (int ks = 0; ks < nks; ++ks) {
;         const bf16* apk = ap + (ks >> 1) * (256 * 32) + 16 * (ks & 1);
;         const bf16x8 a0 = *(const bf16x8*)apk, a1 = *(const bf16x8*)(apk + 32 * 32);
;         const int pb = 16 * ks + 8 * hh;
;         float rs[8];
; #pragma unroll
;         for (int j = 0; j < 8; ++j) rs[j] = rstd[pb + j];
; #pragma unroll
;         for (int nt = 0; nt < 2; ++nt) {
;             const int t = 64 * th + 32 * nt + r; const float* wq = wrow + (size_t)t * 128 + 16 * ks;
;             const f32x4 w0 = *(const f32x4*)wq, w1 = *(const f32x4*)(wq + 4); float bv[8];
; #pragma unroll
;             for (int j = 0; j < 4; ++j) { bv[j] = (pb + j <= t) ? w0[j] * rs[j] : 0.f; bv[4 + j] = (pb + 4 + j <= t) ? w1[j] * rs[4 + j] : 0.f; }
;             const bf16x8 bf = pack8(bv);
;             acc[0][nt] = MFMA32(a0, bf, acc[0][nt]); acc[1][nt] = MFMA32(a1, bf, acc[1][nt]);
;         }
;     }
	v_pk_mul_f32 v[72:73], v[134:135], v[76:77]
	v_cmp_le_u32_e64 s[6:7], v85, v94
	v_cvt_pk_bf16_f32 v72, v72, v73
	v_pk_mul_f32 v[76:77], v[134:135], v[126:127]
	v_cndmask_b32_e64 v73, 0, v72, s[6:7]
	v_cmp_le_u32_e64 s[6:7], v84, v89
	v_lshrrev_b32_e32 v72, 16, v72
	s_nop 0
	v_cndmask_b32_e64 v72, 0, v72, s[6:7]
	v_perm_b32 v124, v72, v73, s52
	v_pk_mul_f32 v[72:73], v[74:75], v[82:83]
	v_cmp_le_u32_e64 s[6:7], v121, v94
	v_cvt_pk_bf16_f32 v72, v72, v73
	v_or_b32_e32 v83, 6, v114
	v_cndmask_b32_e64 v73, 0, v72, s[6:7]
	v_lshrrev_b32_e32 v72, 16, v72
	v_cmp_le_u32_e64 s[6:7], v115, v89
	v_or_b32_e32 v82, 7, v114
	v_pk_mul_f32 v[74:75], v[74:75], v[132:133]
	v_cndmask_b32_e64 v72, 0, v72, s[6:7]
	v_perm_b32 v123, v72, v73, s52
	v_pk_mul_f32 v[72:73], v[136:137], v[78:79]
	v_cmp_le_u32_e64 s[6:7], v83, v94
	v_cvt_pk_bf16_f32 v72, v72, v73
	v_pk_mul_f32 v[78:79], v[136:137], v[128:129]
	v_cndmask_b32_e64 v73, 0, v72, s[6:7]
	v_lshrrev_b32_e32 v72, 16, v72
	v_cmp_le_u32_e64 s[6:7], v82, v89
	s_nop 1
	v_cndmask_b32_e64 v72, 0, v72, s[6:7]
	v_perm_b32 v125, v72, v73, s52
	v_cvt_pk_bf16_f32 v73, v74, v75
	v_cmp_le_u32_e64 s[6:7], v121, v96
	v_cvt_pk_bf16_f32 v72, v80, v81
	v_mfma_f32_32x32x16_bf16 v[48:63], v[64:67], v[122:125], v[48:63]
	v_cndmask_b32_e64 v74, 0, v73, s[6:7]
	v_lshrrev_b32_e32 v73, 16, v73
	v_cmp_le_u32_e64 s[6:7], v115, v87
	v_or_b32_e32 v121, 5, v120
	s_nop 0
	v_cndmask_b32_e64 v73, 0, v73, s[6:7]
	v_perm_b32 v73, v73, v74, s52
	v_cvt_pk_bf16_f32 v74, v76, v77
	v_cmp_le_u32_e64 s[6:7], v85, v96
	v_mfma_f32_32x32x16_bf16 v[16:31], v[68:71], v[122:125], v[16:31]
	s_nop 0
	v_cndmask_b32_e64 v75, 0, v74, s[6:7]
	v_cmp_le_u32_e64 s[6:7], v84, v87
	v_lshrrev_b32_e32 v74, 16, v74
	s_nop 0
	v_cndmask_b32_e64 v74, 0, v74, s[6:7]
	v_perm_b32 v74, v74, v75, s52
	v_cvt_pk_bf16_f32 v75, v78, v79
	v_cmp_le_u32_e64 s[6:7], v83, v96
	s_nop 1
	v_cndmask_b32_e64 v76, 0, v75, s[6:7]
	v_lshrrev_b32_e32 v75, 16, v75
	v_cmp_le_u32_e64 s[6:7], v82, v87
	s_nop 1
	v_cndmask_b32_e64 v75, 0, v75, s[6:7]
	v_perm_b32 v75, v75, v76, s52
	s_and_b32 s6, s9, 0x7fffe000
	s_lshl_b32 s94, s6, 1
	v_mfma_f32_32x32x16_bf16 v[32:47], v[64:67], v[72:75], v[32:47]
	v_lshl_add_u64 v[64:65], v[112:113], 0, s[94:95]
	v_cmp_le_u32_e64 s[6:7], v120, v94
	s_addk_i32 s9, 0x4000
	v_mfma_f32_32x32x16_bf16 v[0:15], v[68:71], v[72:75], v[0:15]
	v_lshl_add_u64 v[72:73], s[12:13], 2, v[92:93]
	v_lshl_add_u64 v[74:75], v[72:73], 0, v[178:179]
	s_nop 4
	v_mov_b32_e32 v68, v216
	v_mov_b32_e32 v69, v217
	v_mov_b32_e32 v70, v218
	v_mov_b32_e32 v71, v219
	s_nop 0
	s_nop 4
	v_mov_b32_e32 v64, v220
	v_mov_b32_e32 v65, v221
	v_mov_b32_e32 v66, v222
	v_mov_b32_e32 v67, v223
	ds_read_b128 v[122:125], v119 offset:192
	s_nop 4
	v_mov_b32_e32 v78, v232
	v_mov_b32_e32 v79, v233
	v_mov_b32_e32 v80, v234
	v_mov_b32_e32 v81, v235
	s_nop 4
	v_mov_b32_e32 v126, v236
	v_mov_b32_e32 v127, v237
	v_mov_b32_e32 v128, v238
	v_mov_b32_e32 v129, v239
	v_lshl_add_u64 v[82:83], v[72:73], 0, v[110:111]
	v_or_b32_e32 v111, 7, v120
	s_add_i32 s12, s12, 64
	s_cmp_lg_u32 s15, 0
	s_waitcnt lgkmcnt(0)
	v_mul_f32_e32 v74, v122, v126
	v_cndmask_b32_e64 v74, 0, v74, s[6:7]
	v_cmp_lt_u32_e64 s[6:7], v120, v94
	v_mul_f32_e32 v75, v123, v127
	v_or_b32_e32 v127, 3, v120
	v_cndmask_b32_e64 v75, 0, v75, s[6:7]
	v_cvt_pk_bf16_f32 v76, v74, v75
	s_nop 4
	v_mov_b32_e32 v72, v240
	v_mov_b32_e32 v73, v241
	v_mov_b32_e32 v74, v242
	v_mov_b32_e32 v75, v243
	s_nop 4
	v_mov_b32_e32 v130, v244
	v_mov_b32_e32 v131, v245
	v_mov_b32_e32 v132, v246
	v_mov_b32_e32 v133, v247
	ds_read_b128 v[82:85], v119 offset:208
	v_cmp_le_u32_e64 s[6:7], v120, v96
	v_add_u32_e32 v119, 0x100, v119
	s_waitcnt lgkmcnt(0)
	v_pk_mul_f32 v[78:79], v[82:83], v[78:79]
	v_pk_mul_f32 v[82:83], v[82:83], v[72:73]
	v_mul_f32_e32 v77, v122, v130
	v_cndmask_b32_e64 v126, 0, v77, s[6:7]
	v_cmp_lt_u32_e64 s[6:7], v120, v96
	v_mul_f32_e32 v77, v123, v131
	v_or_b32_e32 v122, 4, v120
	v_cndmask_b32_e64 v123, 0, v77, s[6:7]
	v_cvt_pk_bf16_f32 v77, v78, v79
	v_cmp_le_u32_e64 s[6:7], v122, v94
	v_or_b32_e32 v130, 2, v120
	v_pk_mul_f32 v[72:73], v[124:125], v[128:129]
	v_cndmask_b32_e64 v78, 0, v77, s[6:7]
	v_cmp_le_u32_e64 s[6:7], v121, v89
	v_lshrrev_b32_e32 v77, 16, v77
	v_cvt_pk_bf16_f32 v72, v72, v73
	v_cndmask_b32_e64 v77, 0, v77, s[6:7]
	v_cmp_le_u32_e64 s[6:7], v130, v94
	v_perm_b32 v78, v77, v78, s52
	v_or_b32_e32 v120, 6, v120
	v_cndmask_b32_e64 v73, 0, v72, s[6:7]
	v_lshrrev_b32_e32 v72, 16, v72
	v_cmp_le_u32_e64 s[6:7], v127, v89
	v_pk_mul_f32 v[114:115], v[124:125], v[132:133]
	s_nop 0
	v_cndmask_b32_e64 v72, 0, v72, s[6:7]
	v_perm_b32 v77, v72, v73, s52
	v_pk_mul_f32 v[72:73], v[84:85], v[80:81]
	v_cmp_le_u32_e64 s[6:7], v120, v94
	v_cvt_pk_bf16_f32 v72, v72, v73
	s_nop 0
	v_cndmask_b32_e64 v73, 0, v72, s[6:7]
	v_lshrrev_b32_e32 v72, 16, v72
	v_cmp_le_u32_e64 s[6:7], v111, v89
	s_nop 1
	v_cndmask_b32_e64 v72, 0, v72, s[6:7]
	v_perm_b32 v79, v72, v73, s52
	v_cvt_pk_bf16_f32 v73, v114, v115
	v_cmp_le_u32_e64 s[6:7], v130, v96
	v_mfma_f32_32x32x16_bf16 v[48:63], v[68:71], v[76:79], v[48:63]
	v_cvt_pk_bf16_f32 v72, v126, v123
	v_mfma_f32_32x32x16_bf16 v[16:31], v[64:67], v[76:79], v[16:31]
	v_mul_f32_e64 v76, v84, v74
	v_mul_f32_e64 v77, v85, v75
	v_cndmask_b32_e64 v74, 0, v73, s[6:7]
	v_lshrrev_b32_e32 v73, 16, v73
	v_cmp_le_u32_e64 s[6:7], v127, v87
	s_nop 1
	v_cndmask_b32_e64 v73, 0, v73, s[6:7]
	v_perm_b32 v73, v73, v74, s52
	v_cvt_pk_bf16_f32 v74, v82, v83
	v_cmp_le_u32_e64 s[6:7], v122, v96
	s_nop 1
	v_cndmask_b32_e64 v75, 0, v74, s[6:7]
	v_cmp_le_u32_e64 s[6:7], v121, v87
	v_lshrrev_b32_e32 v74, 16, v74
	s_nop 0
	v_cndmask_b32_e64 v74, 0, v74, s[6:7]
	v_perm_b32 v74, v74, v75, s52
	v_cvt_pk_bf16_f32 v75, v76, v77
	v_cmp_le_u32_e64 s[6:7], v120, v96
	s_nop 1
	v_cndmask_b32_e64 v76, 0, v75, s[6:7]
	v_lshrrev_b32_e32 v75, 16, v75
	v_cmp_le_u32_e64 s[6:7], v111, v87
	s_nop 1
	v_cndmask_b32_e64 v75, 0, v75, s[6:7]
	v_perm_b32 v75, v75, v76, s52
	s_nop 1
	v_mfma_f32_32x32x16_bf16 v[32:47], v[68:71], v[72:75], v[32:47]
	v_mfma_f32_32x32x16_bf16 v[0:15], v[64:67], v[72:75], v[0:15]
	s_cbranch_scc1 .LBB0_105
; __device__ __forceinline__ unsigned pk2(float lo, float hi) { f32v2 v = {lo, hi}; bf16v2 r = __builtin_convertvector(v, bf16v2); return __builtin_bit_cast(unsigned, r); }
; __device__ __forceinline__ void gmlp_unit(const bf16* GVT, const bf16* U, const float* wsp, const float* bsp, const float* gain, bf16* OGM, int unit, LAS unsigned char* lds, int tid, int wave, int lane) {
;     ...
; #pragma unroll
;     for (int mt = 0; mt < 2; ++mt)
; #pragma unroll
;         for (int nt = 0; nt < 2; ++nt) {
;             const int t = 64 * th + 32 * nt + r; const float bias = bsp[g * 128 + t];
; #pragma unroll
;             for (int gp = 0; gp < 2; ++gp) {
;                 v2u pc[2];
; #pragma unroll
;                 for (int e = 0; e < 2; ++e) { const int q4 = 2 * gp + e;
;                     const int c = g * 64 + mt * 32 + 8 * q4 + 4 * hh;
;                     const f32x4 gn = *(const f32x4*)(gain + c);
;                     const v2u uw = *(const v2u*)(U + (tok0 + t) * 256 + c);
;                     const float v0 = (acc[mt][nt][4 * q4] * gn.x + bias) * bf_lo(uw.x), v1 = (acc[mt][nt][4 * q4 + 1] * gn.y + bias) * bf_hi(uw.x);
;                     const float v2 = (acc[mt][nt][4 * q4 + 2] * gn.z + bias) * bf_lo(uw.y), v3 = (acc[mt][nt][4 * q4 + 3] * gn.w + bias) * bf_hi(uw.y);
;                     pc[e].x = pk2(v0, v1); pc[e].y = pk2(v2, v3); }
;                 *(v4u*)(OGM + (tok0 + t) * 256 + g * 64 + mt * 32 + 8 * (2 * gp + hh)) = pair_widen(pc[0], pc[1], hh);
	v_mov_b32_e32 v65, s11
	v_or_b32_e32 v64, s10, v94
	v_lshlrev_b64 v[76:77], 9, v[64:65]
	v_lshl_add_u64 v[64:65], v[106:107], 0, v[76:77]
	v_mov_b32_e32 v249, s11
	v_or_b32_e32 v248, s10, v96
	v_lshlrev_b64 v[248:249], 9, v[248:249]
	v_lshl_add_u64 v[182:183], v[106:107], 0, v[248:249]
	global_load_dwordx4 v[192:195], v[98:99], off
	global_load_dwordx4 v[196:199], v[98:99], off offset:32
	global_load_dwordx4 v[200:203], v[98:99], off offset:64
	global_load_dwordx4 v[204:207], v[98:99], off offset:96
	global_load_dwordx4 v[208:211], v[98:99], off offset:128
	global_load_dwordx4 v[212:215], v[98:99], off offset:160
	global_load_dwordx4 v[216:219], v[98:99], off offset:192
	global_load_dwordx4 v[220:223], v[98:99], off offset:224
	global_load_dword v180, v[100:101], off
	global_load_dword v181, v[102:103], off offset:128
	global_load_dwordx2 v[148:149], v[64:65], off
	global_load_dwordx2 v[150:151], v[64:65], off offset:16
	global_load_dwordx2 v[152:153], v[64:65], off offset:32
	global_load_dwordx2 v[154:155], v[64:65], off offset:48
	global_load_dwordx2 v[156:157], v[64:65], off offset:64
	global_load_dwordx2 v[158:159], v[64:65], off offset:80
	global_load_dwordx2 v[160:161], v[64:65], off offset:96
	global_load_dwordx2 v[162:163], v[64:65], off offset:112
	global_load_dwordx2 v[232:233], v[182:183], off
	global_load_dwordx2 v[234:235], v[182:183], off offset:16
	global_load_dwordx2 v[236:237], v[182:183], off offset:32
	global_load_dwordx2 v[238:239], v[182:183], off offset:48
	global_load_dwordx2 v[240:241], v[182:183], off offset:64
	global_load_dwordx2 v[242:243], v[182:183], off offset:80
	global_load_dwordx2 v[244:245], v[182:183], off offset:96
	global_load_dwordx2 v[246:247], v[182:183], off offset:112
	s_waitcnt vmcnt(0)
	s_nop 1
	v_mov_b32_e32 v74, v180
	s_nop 1
	v_mov_b32_e32 v66, v192
	v_mov_b32_e32 v67, v193
	v_mov_b32_e32 v68, v194
	v_mov_b32_e32 v69, v195
	s_nop 1
	v_mov_b32_e32 v70, v196
	v_mov_b32_e32 v71, v197
	v_mov_b32_e32 v72, v198
	v_mov_b32_e32 v73, v199
	s_nop 1
	v_mov_b32_e32 v78, v148
	v_mov_b32_e32 v79, v149
	s_nop 1
	v_mov_b32_e32 v80, v150
	v_mov_b32_e32 v81, v151
	s_add_i32 s8, s8, s82
	s_cmpk_gt_i32 s8, 0xff
	v_pk_fma_f32 v[50:51], v[50:51], v[68:69], v[74:75] op_sel_hi:[1,1,0]
	v_pk_fma_f32 v[54:55], v[54:55], v[72:73], v[74:75] op_sel_hi:[1,1,0]
	v_lshlrev_b32_e32 v68, 16, v79
	v_and_b32_e32 v69, 0xffff0000, v79
	v_lshlrev_b32_e32 v72, 16, v81
	v_and_b32_e32 v73, 0xffff0000, v81
	v_pk_fma_f32 v[48:49], v[48:49], v[66:67], v[74:75] op_sel_hi:[1,1,0]
	v_pk_fma_f32 v[52:53], v[52:53], v[70:71], v[74:75] op_sel_hi:[1,1,0]
	v_lshlrev_b32_e32 v66, 16, v78
	v_and_b32_e32 v67, 0xffff0000, v78
	v_lshlrev_b32_e32 v70, 16, v80
	v_and_b32_e32 v71, 0xffff0000, v80
	v_pk_mul_f32 v[50:51], v[50:51], v[68:69]
	v_pk_mul_f32 v[54:55], v[54:55], v[72:73]
	v_pk_mul_f32 v[48:49], v[48:49], v[66:67]
	v_pk_mul_f32 v[52:53], v[52:53], v[70:71]
	v_cvt_pk_bf16_f32 v50, v50, v51
	v_cvt_pk_bf16_f32 v51, v54, v55
	v_cvt_pk_bf16_f32 v66, v48, v49
	v_cvt_pk_bf16_f32 v52, v52, v53
	v_cndmask_b32_e64 v48, v50, v51, s[4:5]
	ds_bpermute_b32 v54, v117, v48
	v_cndmask_b32_e64 v48, v66, v52, s[4:5]
	ds_bpermute_b32 v55, v117, v48
	v_lshl_add_u64 v[48:49], v[108:109], 0, v[76:77]
	v_mov_b32_e32 v73, s11
	s_waitcnt lgkmcnt(1)
	v_cndmask_b32_e64 v53, v51, v54, s[4:5]
	v_cndmask_b32_e64 v51, v54, v50, s[4:5]
	s_waitcnt lgkmcnt(0)
	v_cndmask_b32_e64 v52, v52, v55, s[4:5]
	v_cndmask_b32_e64 v50, v55, v66, s[4:5]
	global_store_dwordx4 v[48:49], v[50:53], off
	s_nop 1
	v_mov_b32_e32 v50, v200
	v_mov_b32_e32 v51, v201
	v_mov_b32_e32 v52, v202
	v_mov_b32_e32 v53, v203
	s_nop 0
	s_nop 1
	v_mov_b32_e32 v54, v152
	v_mov_b32_e32 v55, v153
	s_nop 1
	v_mov_b32_e32 v66, v204
	v_mov_b32_e32 v67, v205
	v_mov_b32_e32 v68, v206
	v_mov_b32_e32 v69, v207
	s_nop 1
	v_mov_b32_e32 v70, v154
	v_mov_b32_e32 v71, v155
	v_or_b32_e32 v72, s10, v96
	v_pk_fma_f32 v[50:51], v[56:57], v[50:51], v[74:75] op_sel_hi:[1,1,0]
	v_lshlrev_b32_e32 v56, 16, v54
	v_and_b32_e32 v57, 0xffff0000, v54
	v_pk_fma_f32 v[52:53], v[58:59], v[52:53], v[74:75] op_sel_hi:[1,1,0]
	v_lshlrev_b32_e32 v54, 16, v55
	v_and_b32_e32 v55, 0xffff0000, v55
	v_pk_fma_f32 v[58:59], v[60:61], v[66:67], v[74:75] op_sel_hi:[1,1,0]
	v_pk_fma_f32 v[62:63], v[62:63], v[68:69], v[74:75] op_sel_hi:[1,1,0]
	v_lshlrev_b32_e32 v66, 16, v71
	v_and_b32_e32 v67, 0xffff0000, v71
	v_lshlrev_b32_e32 v60, 16, v70
	v_and_b32_e32 v61, 0xffff0000, v70
	v_pk_mul_f32 v[50:51], v[50:51], v[56:57]
	v_pk_mul_f32 v[52:53], v[52:53], v[54:55]
	v_pk_mul_f32 v[56:57], v[62:63], v[66:67]
	v_pk_mul_f32 v[54:55], v[58:59], v[60:61]
	v_cvt_pk_bf16_f32 v52, v52, v53
	v_cvt_pk_bf16_f32 v53, v56, v57
	v_cvt_pk_bf16_f32 v58, v50, v51
	v_cvt_pk_bf16_f32 v54, v54, v55
	v_cndmask_b32_e64 v50, v52, v53, s[4:5]
	ds_bpermute_b32 v56, v117, v50
	v_cndmask_b32_e64 v50, v58, v54, s[4:5]
	ds_bpermute_b32 v57, v117, v50
	v_lshlrev_b64 v[60:61], 9, v[72:73]
	v_lshl_add_u64 v[50:51], v[106:107], 0, v[60:61]
	s_waitcnt lgkmcnt(1)
	v_cndmask_b32_e64 v55, v53, v56, s[4:5]
	v_cndmask_b32_e64 v53, v56, v52, s[4:5]
	s_waitcnt lgkmcnt(0)
; __device__ __forceinline__ unsigned pk2(float lo, float hi) { f32v2 v = {lo, hi}; bf16v2 r = __builtin_convertvector(v, bf16v2); return __builtin_bit_cast(unsigned, r); }
; __device__ __forceinline__ void gmlp_unit(const bf16* GVT, const bf16* U, const float* wsp, const float* bsp, const float* gain, bf16* OGM, int unit, LAS unsigned char* lds, int tid, int wave, int lane) {
;     ...
; #pragma unroll
;     for (int mt = 0; mt < 2; ++mt)
; #pragma unroll
;         for (int nt = 0; nt < 2; ++nt) {
;             const int t = 64 * th + 32 * nt + r; const float bias = bsp[g * 128 + t];
; #pragma unroll
;             for (int gp = 0; gp < 2; ++gp) {
;                 v2u pc[2];
; #pragma unroll
;                 for (int e = 0; e < 2; ++e) { const int q4 = 2 * gp + e;
;                     const int c = g * 64 + mt * 32 + 8 * q4 + 4 * hh;
;                     const f32x4 gn = *(const f32x4*)(gain + c);
;                     const v2u uw = *(const v2u*)(U + (tok0 + t) * 256 + c);
;                     const float v0 = (acc[mt][nt][4 * q4] * gn.x + bias) * bf_lo(uw.x), v1 = (acc[mt][nt][4 * q4 + 1] * gn.y + bias) * bf_hi(uw.x);
;                     const float v2 = (acc[mt][nt][4 * q4 + 2] * gn.z + bias) * bf_lo(uw.y), v3 = (acc[mt][nt][4 * q4 + 3] * gn.w + bias) * bf_hi(uw.y);
;                     pc[e].x = pk2(v0, v1); pc[e].y = pk2(v2, v3); }
;                 *(v4u*)(OGM + (tok0 + t) * 256 + g * 64 + mt * 32 + 8 * (2 * gp + hh)) = pair_widen(pc[0], pc[1], hh);
	v_cndmask_b32_e64 v54, v54, v57, s[4:5]
	v_cndmask_b32_e64 v52, v57, v58, s[4:5]
	global_store_dwordx4 v[48:49], v[52:55], off offset:32
	s_nop 1
	v_mov_b32_e32 v62, v181
	s_nop 0
	s_nop 1
	v_mov_b32_e32 v52, v192
	v_mov_b32_e32 v53, v193
	v_mov_b32_e32 v54, v194
	v_mov_b32_e32 v55, v195
	s_nop 1
	v_mov_b32_e32 v66, v232
	v_mov_b32_e32 v67, v233
	s_nop 1
	v_mov_b32_e32 v56, v196
	v_mov_b32_e32 v57, v197
	v_mov_b32_e32 v58, v198
	v_mov_b32_e32 v59, v199
	s_nop 1
	v_mov_b32_e32 v68, v234
	v_mov_b32_e32 v69, v235
	v_pk_fma_f32 v[34:35], v[34:35], v[54:55], v[62:63] op_sel_hi:[1,1,0]
	v_lshlrev_b32_e32 v54, 16, v67
	v_and_b32_e32 v55, 0xffff0000, v67
	v_pk_fma_f32 v[38:39], v[38:39], v[58:59], v[62:63] op_sel_hi:[1,1,0]
	v_lshlrev_b32_e32 v58, 16, v69
	v_and_b32_e32 v59, 0xffff0000, v69
	v_pk_fma_f32 v[32:33], v[32:33], v[52:53], v[62:63] op_sel_hi:[1,1,0]
	v_lshlrev_b32_e32 v52, 16, v66
	v_and_b32_e32 v53, 0xffff0000, v66
	v_pk_fma_f32 v[36:37], v[36:37], v[56:57], v[62:63] op_sel_hi:[1,1,0]
	v_lshlrev_b32_e32 v56, 16, v68
	v_and_b32_e32 v57, 0xffff0000, v68
	v_pk_mul_f32 v[34:35], v[34:35], v[54:55]
	v_pk_mul_f32 v[38:39], v[38:39], v[58:59]
	v_pk_mul_f32 v[32:33], v[32:33], v[52:53]
	v_pk_mul_f32 v[36:37], v[36:37], v[56:57]
	v_cvt_pk_bf16_f32 v34, v34, v35
	v_cvt_pk_bf16_f32 v35, v38, v39
	v_cvt_pk_bf16_f32 v52, v32, v33
	v_cvt_pk_bf16_f32 v36, v36, v37
	v_cndmask_b32_e64 v32, v34, v35, s[4:5]
	ds_bpermute_b32 v38, v117, v32
	v_cndmask_b32_e64 v32, v52, v36, s[4:5]
	ds_bpermute_b32 v39, v117, v32
	v_lshl_add_u64 v[32:33], v[108:109], 0, v[60:61]
	s_waitcnt lgkmcnt(1)
	v_cndmask_b32_e64 v37, v35, v38, s[4:5]
	v_cndmask_b32_e64 v35, v38, v34, s[4:5]
	s_waitcnt lgkmcnt(0)
	v_cndmask_b32_e64 v36, v36, v39, s[4:5]
	v_cndmask_b32_e64 v34, v39, v52, s[4:5]
	global_store_dwordx4 v[32:33], v[34:37], off
	s_nop 1
	v_mov_b32_e32 v34, v200
	v_mov_b32_e32 v35, v201
	v_mov_b32_e32 v36, v202
	v_mov_b32_e32 v37, v203
	s_nop 0
	s_nop 1
	v_mov_b32_e32 v38, v236
	v_mov_b32_e32 v39, v237
	s_nop 1
	v_mov_b32_e32 v52, v204
	v_mov_b32_e32 v53, v205
	v_mov_b32_e32 v54, v206
	v_mov_b32_e32 v55, v207
	s_nop 1
	v_mov_b32_e32 v56, v238
	v_mov_b32_e32 v57, v239
	v_pk_fma_f32 v[34:35], v[40:41], v[34:35], v[62:63] op_sel_hi:[1,1,0]
	v_lshlrev_b32_e32 v40, 16, v38
	v_and_b32_e32 v41, 0xffff0000, v38
	v_pk_fma_f32 v[36:37], v[42:43], v[36:37], v[62:63] op_sel_hi:[1,1,0]
	v_lshlrev_b32_e32 v38, 16, v39
	v_and_b32_e32 v39, 0xffff0000, v39
	v_pk_fma_f32 v[42:43], v[44:45], v[52:53], v[62:63] op_sel_hi:[1,1,0]
	v_lshlrev_b32_e32 v44, 16, v56
	v_and_b32_e32 v45, 0xffff0000, v56
	v_pk_fma_f32 v[46:47], v[46:47], v[54:55], v[62:63] op_sel_hi:[1,1,0]
	v_lshlrev_b32_e32 v52, 16, v57
	v_and_b32_e32 v53, 0xffff0000, v57
	v_pk_mul_f32 v[34:35], v[34:35], v[40:41]
	v_pk_mul_f32 v[36:37], v[36:37], v[38:39]
	v_pk_mul_f32 v[38:39], v[42:43], v[44:45]
	v_pk_mul_f32 v[40:41], v[46:47], v[52:53]
	v_cvt_pk_bf16_f32 v34, v34, v35
	v_cvt_pk_bf16_f32 v35, v36, v37
	v_cvt_pk_bf16_f32 v36, v38, v39
	v_cvt_pk_bf16_f32 v37, v40, v41
	v_cndmask_b32_e64 v38, v35, v37, s[4:5]
	v_cndmask_b32_e64 v39, v34, v36, s[4:5]
	ds_bpermute_b32 v38, v117, v38
	ds_bpermute_b32 v39, v117, v39
	s_waitcnt lgkmcnt(1)
	v_cndmask_b32_e64 v37, v37, v38, s[4:5]
	v_cndmask_b32_e64 v35, v38, v35, s[4:5]
	s_waitcnt lgkmcnt(0)
	v_cndmask_b32_e64 v36, v36, v39, s[4:5]
	v_cndmask_b32_e64 v34, v39, v34, s[4:5]
	global_store_dwordx4 v[32:33], v[34:37], off offset:32
	s_nop 1
	v_mov_b32_e32 v42, v180
	s_nop 0
	s_nop 1
	v_mov_b32_e32 v34, v208
	v_mov_b32_e32 v35, v209
	v_mov_b32_e32 v36, v210
	v_mov_b32_e32 v37, v211
	s_nop 1
	v_mov_b32_e32 v44, v156
	v_mov_b32_e32 v45, v157
	s_nop 1
	v_mov_b32_e32 v38, v212
	v_mov_b32_e32 v39, v213
	v_mov_b32_e32 v40, v214
	v_mov_b32_e32 v41, v215
	s_nop 1
	v_mov_b32_e32 v46, v158
	v_mov_b32_e32 v47, v159
	v_pk_fma_f32 v[16:17], v[16:17], v[34:35], v[42:43] op_sel_hi:[1,1,0]
	v_lshlrev_b32_e32 v34, 16, v44
	v_and_b32_e32 v35, 0xffff0000, v44
	v_pk_fma_f32 v[18:19], v[18:19], v[36:37], v[42:43] op_sel_hi:[1,1,0]
	v_lshlrev_b32_e32 v36, 16, v45
	v_and_b32_e32 v37, 0xffff0000, v45
	v_pk_fma_f32 v[20:21], v[20:21], v[38:39], v[42:43] op_sel_hi:[1,1,0]
	v_lshlrev_b32_e32 v38, 16, v46
	v_and_b32_e32 v39, 0xffff0000, v46
	v_pk_fma_f32 v[22:23], v[22:23], v[40:41], v[42:43] op_sel_hi:[1,1,0]
	v_lshlrev_b32_e32 v40, 16, v47
	v_and_b32_e32 v41, 0xffff0000, v47
	v_pk_mul_f32 v[16:17], v[16:17], v[34:35]
	v_pk_mul_f32 v[18:19], v[18:19], v[36:37]
	v_pk_mul_f32 v[20:21], v[20:21], v[38:39]
	v_pk_mul_f32 v[22:23], v[22:23], v[40:41]
	v_cvt_pk_bf16_f32 v16, v16, v17
	v_cvt_pk_bf16_f32 v17, v18, v19
	v_cvt_pk_bf16_f32 v18, v20, v21
	v_cvt_pk_bf16_f32 v19, v22, v23
	v_cndmask_b32_e64 v20, v17, v19, s[4:5]
	v_cndmask_b32_e64 v21, v16, v18, s[4:5]
	ds_bpermute_b32 v20, v117, v20
	ds_bpermute_b32 v21, v117, v21
	s_waitcnt lgkmcnt(1)
	v_cndmask_b32_e64 v19, v19, v20, s[4:5]
	v_cndmask_b32_e64 v17, v20, v17, s[4:5]
	s_waitcnt lgkmcnt(0)
; __device__ __forceinline__ unsigned pk2(float lo, float hi) { f32v2 v = {lo, hi}; bf16v2 r = __builtin_convertvector(v, bf16v2); return __builtin_bit_cast(unsigned, r); }
; __device__ __forceinline__ void gmlp_unit(const bf16* GVT, const bf16* U, const float* wsp, const float* bsp, const float* gain, bf16* OGM, int unit, LAS unsigned char* lds, int tid, int wave, int lane) {
;     ...
; #pragma unroll
;     for (int mt = 0; mt < 2; ++mt)
; #pragma unroll
;         for (int nt = 0; nt < 2; ++nt) {
;             const int t = 64 * th + 32 * nt + r; const float bias = bsp[g * 128 + t];
; #pragma unroll
;             for (int gp = 0; gp < 2; ++gp) {
;                 v2u pc[2];
; #pragma unroll
;                 for (int e = 0; e < 2; ++e) { const int q4 = 2 * gp + e;
;                     const int c = g * 64 + mt * 32 + 8 * q4 + 4 * hh;
;                     const f32x4 gn = *(const f32x4*)(gain + c);
;                     const v2u uw = *(const v2u*)(U + (tok0 + t) * 256 + c);
;                     const float v0 = (acc[mt][nt][4 * q4] * gn.x + bias) * bf_lo(uw.x), v1 = (acc[mt][nt][4 * q4 + 1] * gn.y + bias) * bf_hi(uw.x);
;                     const float v2 = (acc[mt][nt][4 * q4 + 2] * gn.z + bias) * bf_lo(uw.y), v3 = (acc[mt][nt][4 * q4 + 3] * gn.w + bias) * bf_hi(uw.y);
;                     pc[e].x = pk2(v0, v1); pc[e].y = pk2(v2, v3); }
;                 *(v4u*)(OGM + (tok0 + t) * 256 + g * 64 + mt * 32 + 8 * (2 * gp + hh)) = pair_widen(pc[0], pc[1], hh);
;             }
;         }
	v_cndmask_b32_e64 v18, v18, v21, s[4:5]
	v_cndmask_b32_e64 v16, v21, v16, s[4:5]
	global_store_dwordx4 v[48:49], v[16:19], off offset:64
	s_nop 1
	v_mov_b32_e32 v16, v216
	v_mov_b32_e32 v17, v217
	v_mov_b32_e32 v18, v218
	v_mov_b32_e32 v19, v219
	s_nop 0
	s_nop 1
	v_mov_b32_e32 v34, v160
	v_mov_b32_e32 v35, v161
	s_nop 1
	v_mov_b32_e32 v20, v220
	v_mov_b32_e32 v21, v221
	v_mov_b32_e32 v22, v222
	v_mov_b32_e32 v23, v223
	s_nop 1
	v_mov_b32_e32 v36, v162
	v_mov_b32_e32 v37, v163
	v_pk_fma_f32 v[16:17], v[24:25], v[16:17], v[42:43] op_sel_hi:[1,1,0]
	v_lshlrev_b32_e32 v24, 16, v34
	v_and_b32_e32 v25, 0xffff0000, v34
	v_pk_fma_f32 v[18:19], v[26:27], v[18:19], v[42:43] op_sel_hi:[1,1,0]
	v_lshlrev_b32_e32 v26, 16, v35
	v_and_b32_e32 v27, 0xffff0000, v35
	v_pk_fma_f32 v[20:21], v[28:29], v[20:21], v[42:43] op_sel_hi:[1,1,0]
	v_lshlrev_b32_e32 v28, 16, v36
	v_and_b32_e32 v29, 0xffff0000, v36
	v_pk_fma_f32 v[22:23], v[30:31], v[22:23], v[42:43] op_sel_hi:[1,1,0]
	v_lshlrev_b32_e32 v30, 16, v37
	v_and_b32_e32 v31, 0xffff0000, v37
	v_pk_mul_f32 v[16:17], v[16:17], v[24:25]
	v_pk_mul_f32 v[18:19], v[18:19], v[26:27]
	v_pk_mul_f32 v[20:21], v[20:21], v[28:29]
	v_pk_mul_f32 v[22:23], v[22:23], v[30:31]
	v_cvt_pk_bf16_f32 v16, v16, v17
	v_cvt_pk_bf16_f32 v17, v18, v19
	v_cvt_pk_bf16_f32 v18, v20, v21
	v_cvt_pk_bf16_f32 v19, v22, v23
	v_cndmask_b32_e64 v20, v17, v19, s[4:5]
	v_cndmask_b32_e64 v21, v16, v18, s[4:5]
	ds_bpermute_b32 v20, v117, v20
	ds_bpermute_b32 v21, v117, v21
	s_waitcnt lgkmcnt(1)
	v_cndmask_b32_e64 v19, v19, v20, s[4:5]
	v_cndmask_b32_e64 v17, v20, v17, s[4:5]
	s_waitcnt lgkmcnt(0)
	v_cndmask_b32_e64 v18, v18, v21, s[4:5]
	v_cndmask_b32_e64 v16, v21, v16, s[4:5]
	global_store_dwordx4 v[48:49], v[16:19], off offset:96
	s_nop 1
	v_mov_b32_e32 v24, v181
	s_nop 0
	s_nop 1
	v_mov_b32_e32 v16, v208
	v_mov_b32_e32 v17, v209
	v_mov_b32_e32 v18, v210
	v_mov_b32_e32 v19, v211
	s_nop 1
	v_mov_b32_e32 v26, v240
	v_mov_b32_e32 v27, v241
	s_nop 1
	v_mov_b32_e32 v20, v212
	v_mov_b32_e32 v21, v213
	v_mov_b32_e32 v22, v214
	v_mov_b32_e32 v23, v215
	s_nop 1
	v_mov_b32_e32 v28, v242
	v_mov_b32_e32 v29, v243
	v_pk_fma_f32 v[0:1], v[0:1], v[16:17], v[24:25] op_sel_hi:[1,1,0]
	v_lshlrev_b32_e32 v16, 16, v26
	v_and_b32_e32 v17, 0xffff0000, v26
	v_pk_fma_f32 v[2:3], v[2:3], v[18:19], v[24:25] op_sel_hi:[1,1,0]
	v_lshlrev_b32_e32 v18, 16, v27
	v_and_b32_e32 v19, 0xffff0000, v27
	v_pk_fma_f32 v[4:5], v[4:5], v[20:21], v[24:25] op_sel_hi:[1,1,0]
	v_lshlrev_b32_e32 v20, 16, v28
	v_and_b32_e32 v21, 0xffff0000, v28
	v_pk_fma_f32 v[6:7], v[6:7], v[22:23], v[24:25] op_sel_hi:[1,1,0]
	v_lshlrev_b32_e32 v22, 16, v29
	v_and_b32_e32 v23, 0xffff0000, v29
	v_pk_mul_f32 v[0:1], v[0:1], v[16:17]
	v_pk_mul_f32 v[2:3], v[2:3], v[18:19]
	v_pk_mul_f32 v[4:5], v[4:5], v[20:21]
	v_pk_mul_f32 v[6:7], v[6:7], v[22:23]
	v_cvt_pk_bf16_f32 v0, v0, v1
	v_cvt_pk_bf16_f32 v1, v2, v3
	v_cvt_pk_bf16_f32 v2, v4, v5
	v_cvt_pk_bf16_f32 v3, v6, v7
	v_cndmask_b32_e64 v4, v1, v3, s[4:5]
	v_cndmask_b32_e64 v5, v0, v2, s[4:5]
	ds_bpermute_b32 v4, v117, v4
	ds_bpermute_b32 v5, v117, v5
	s_waitcnt lgkmcnt(1)
	v_cndmask_b32_e64 v3, v3, v4, s[4:5]
	v_cndmask_b32_e64 v1, v4, v1, s[4:5]
	s_waitcnt lgkmcnt(0)
	v_cndmask_b32_e64 v2, v2, v5, s[4:5]
	v_cndmask_b32_e64 v0, v5, v0, s[4:5]
	global_store_dwordx4 v[32:33], v[0:3], off offset:64
	s_nop 1
	v_mov_b32_e32 v0, v216
	v_mov_b32_e32 v1, v217
	v_mov_b32_e32 v2, v218
	v_mov_b32_e32 v3, v219
	s_nop 0
	s_nop 1
	v_mov_b32_e32 v16, v244
	v_mov_b32_e32 v17, v245
	s_nop 1
	v_mov_b32_e32 v4, v220
	v_mov_b32_e32 v5, v221
	v_mov_b32_e32 v6, v222
	v_mov_b32_e32 v7, v223
	s_nop 1
	v_mov_b32_e32 v18, v246
	v_mov_b32_e32 v19, v247
	v_pk_fma_f32 v[0:1], v[8:9], v[0:1], v[24:25] op_sel_hi:[1,1,0]
	v_lshlrev_b32_e32 v8, 16, v16
	v_and_b32_e32 v9, 0xffff0000, v16
	v_pk_fma_f32 v[2:3], v[10:11], v[2:3], v[24:25] op_sel_hi:[1,1,0]
	v_lshlrev_b32_e32 v10, 16, v17
	v_and_b32_e32 v11, 0xffff0000, v17
	v_pk_fma_f32 v[4:5], v[12:13], v[4:5], v[24:25] op_sel_hi:[1,1,0]
	v_lshlrev_b32_e32 v12, 16, v18
	v_and_b32_e32 v13, 0xffff0000, v18
	v_pk_fma_f32 v[6:7], v[14:15], v[6:7], v[24:25] op_sel_hi:[1,1,0]
	v_lshlrev_b32_e32 v14, 16, v19
	v_and_b32_e32 v15, 0xffff0000, v19
	v_pk_mul_f32 v[0:1], v[0:1], v[8:9]
	v_pk_mul_f32 v[2:3], v[2:3], v[10:11]
	v_pk_mul_f32 v[4:5], v[4:5], v[12:13]
	v_pk_mul_f32 v[6:7], v[6:7], v[14:15]
	v_cvt_pk_bf16_f32 v0, v0, v1
	v_cvt_pk_bf16_f32 v1, v2, v3
	v_cvt_pk_bf16_f32 v2, v4, v5
	v_cvt_pk_bf16_f32 v3, v6, v7
	v_cndmask_b32_e64 v4, v1, v3, s[4:5]
	v_cndmask_b32_e64 v5, v0, v2, s[4:5]
	ds_bpermute_b32 v4, v117, v4
	ds_bpermute_b32 v5, v117, v5
	s_waitcnt lgkmcnt(1)
	v_cndmask_b32_e64 v3, v3, v4, s[4:5]
	v_cndmask_b32_e64 v1, v4, v1, s[4:5]
	s_waitcnt lgkmcnt(0)
	v_cndmask_b32_e64 v2, v2, v5, s[4:5]
	v_cndmask_b32_e64 v0, v5, v0, s[4:5]
	global_store_dwordx4 v[32:33], v[0:3], off offset:96
	s_barrier
	s_cbranch_scc0 .LBB0_102
